# plus permlane32_swap for xor32 max exchange, paired compares in top-k radix select, shortened all-ballot tests
# speedup vs baseline: 1.0127x; 1.0127x over previous
; DI float fexp2(float x) { return __builtin_amdgcn_exp2f(x); }
; DI bool soft_core(f32x16& s, float base, float slope2, bool boundary, int tmk8, int wlim, float& mref, bool& seen, float& l, float& alpha) {
;     ...
;     float mt = fmaxf(fmaxf(s[0], s[1]), fmaxf(s[2], s[3]));
; #pragma unroll
;     for (int j = 4; j < 16; j += 4) mt = fmaxf(mt, fmaxf(fmaxf(s[j], s[j + 1]), fmaxf(s[j + 2], s[j + 3])));
;     mt = fmaxf(mt, __shfl_xor(mt, 32));
;     const bool valid = mt > -1e30f, rebase = (mt > 8.f) || (!seen && valid);
;     const bool any = __any(rebase);
;     alpha = 1.f;
;     if (any) {
;         const float delta = rebase ? mt : 0.f;
; #pragma unroll
;         for (int j = 0; j < 16; ++j) s[j] -= delta;
;         alpha = seen ? fexp2(-delta) : 1.f; mref += delta; l *= alpha;
;     }
.LBB0_323:
	v_max3_f32 v0, v10, v11, v8
	v_max3_f32 v98, v9, v12, v13
	v_max3_f32 v99, v14, v15, v96
	v_max3_f32 v100, v97, v6, v7
	v_max3_f32 v0, v0, v2, v3
	v_max3_f32 v98, v98, v4, v5
	v_max3_f32 v99, v99, v100, v98
	v_max_f32_e32 v0, v0, v99
	v_mov_b32_e32 v98, v0
	s_mov_b64 s[18:19], -1
	s_nop 1
	v_permlane32_swap_b32_e32 v0, v98
	v_max_f32_e32 v0, v0, v98
	v_cmp_lt_f32_e64 s[10:11], s67, v0
	v_cmp_nlt_f32_e32 vcc, s68, v0
	s_and_saveexec_b64 s[2:3], vcc
	s_xor_b64 s[18:19], s[54:55], -1
	s_and_b64 s[18:19], s[10:11], s[18:19]
	s_orn2_b64 s[18:19], s[18:19], exec
	s_or_b64 exec, exec, s[2:3]
	v_cndmask_b32_e64 v98, 0, 1, s[18:19]
	v_cmp_ne_u32_e32 vcc, 0, v98
	s_cmp_lg_u64 vcc, 0
	s_cselect_b64 s[2:3], -1, 0
	s_cbranch_vccz .LBB0_346
	v_cndmask_b32_e64 v98, 0, v0, s[18:19]
	v_exp_f32_e64 v0, -v98
	v_pk_add_f32 v[10:11], v[10:11], v[98:99] op_sel_hi:[1,0] neg_lo:[0,1] neg_hi:[0,1]
	v_pk_add_f32 v[8:9], v[8:9], v[98:99] op_sel_hi:[1,0] neg_lo:[0,1] neg_hi:[0,1]
	v_pk_add_f32 v[12:13], v[12:13], v[98:99] op_sel_hi:[1,0] neg_lo:[0,1] neg_hi:[0,1]
	v_cndmask_b32_e64 v0, 1.0, v0, s[54:55]
	v_pk_add_f32 v[14:15], v[14:15], v[98:99] op_sel_hi:[1,0] neg_lo:[0,1] neg_hi:[0,1]
	v_pk_add_f32 v[96:97], v[96:97], v[98:99] op_sel_hi:[1,0] neg_lo:[0,1] neg_hi:[0,1]
	v_pk_add_f32 v[6:7], v[6:7], v[98:99] op_sel_hi:[1,0] neg_lo:[0,1] neg_hi:[0,1]
	v_pk_add_f32 v[2:3], v[2:3], v[98:99] op_sel_hi:[1,0] neg_lo:[0,1] neg_hi:[0,1]
	v_pk_add_f32 v[4:5], v[4:5], v[98:99] op_sel_hi:[1,0] neg_lo:[0,1] neg_hi:[0,1]
	v_add_f32_e32 v186, v186, v98
	v_mul_f32_e32 v155, v155, v0
	s_andn2_b64 vcc, exec, s[2:3]
	s_cbranch_vccnz .LBB0_328

; DI float fexp2(float x) { return __builtin_amdgcn_exp2f(x); }
; DI bool soft_core(f32x16& s, float base, float slope2, bool boundary, int tmk8, int wlim, float& mref, bool& seen, float& l, float& alpha) {
;     ...
;     float mt = fmaxf(fmaxf(s[0], s[1]), fmaxf(s[2], s[3]));
; #pragma unroll
;     for (int j = 4; j < 16; j += 4) mt = fmaxf(mt, fmaxf(fmaxf(s[j], s[j + 1]), fmaxf(s[j + 2], s[j + 3])));
;     mt = fmaxf(mt, __shfl_xor(mt, 32));
;     const bool valid = mt > -1e30f, rebase = (mt > 8.f) || (!seen && valid);
;     const bool any = __any(rebase);
;     alpha = 1.f;
;     if (any) {
;         const float delta = rebase ? mt : 0.f;
; #pragma unroll
;         for (int j = 0; j < 16; ++j) s[j] -= delta;
;         alpha = seen ? fexp2(-delta) : 1.f; mref += delta; l *= alpha;
;     }
.LBB0_331:
	v_max3_f32 v0, v10, v11, v8
	v_max3_f32 v82, v9, v12, v13
	v_max3_f32 v83, v14, v15, v80
	v_max3_f32 v84, v81, v6, v7
	v_max3_f32 v0, v0, v2, v3
	v_max3_f32 v82, v82, v4, v5
	v_max3_f32 v83, v83, v84, v82
	v_max_f32_e32 v0, v0, v83
	v_mov_b32_e32 v82, v0
	s_mov_b64 s[18:19], -1
	s_nop 1
	v_permlane32_swap_b32_e32 v0, v82
	v_max_f32_e32 v0, v0, v82
	v_cmp_lt_f32_e64 s[10:11], s67, v0
	v_cmp_nlt_f32_e32 vcc, s68, v0
	s_and_saveexec_b64 s[0:1], vcc
	s_xor_b64 s[18:19], s[2:3], -1
	s_and_b64 s[18:19], s[10:11], s[18:19]
	s_orn2_b64 s[18:19], s[18:19], exec
	s_or_b64 exec, exec, s[0:1]
	v_cndmask_b32_e64 v82, 0, 1, s[18:19]
	v_cmp_ne_u32_e32 vcc, 0, v82
	s_cmp_lg_u64 vcc, 0
	s_cselect_b64 s[0:1], -1, 0
	s_cbranch_vccz .LBB0_345
	v_cndmask_b32_e64 v82, 0, v0, s[18:19]
	v_exp_f32_e64 v0, -v82
	v_pk_add_f32 v[10:11], v[10:11], v[82:83] op_sel_hi:[1,0] neg_lo:[0,1] neg_hi:[0,1]
	v_pk_add_f32 v[8:9], v[8:9], v[82:83] op_sel_hi:[1,0] neg_lo:[0,1] neg_hi:[0,1]
	v_pk_add_f32 v[12:13], v[12:13], v[82:83] op_sel_hi:[1,0] neg_lo:[0,1] neg_hi:[0,1]
	v_cndmask_b32_e64 v0, 1.0, v0, s[2:3]
	v_pk_add_f32 v[14:15], v[14:15], v[82:83] op_sel_hi:[1,0] neg_lo:[0,1] neg_hi:[0,1]
	v_pk_add_f32 v[80:81], v[80:81], v[82:83] op_sel_hi:[1,0] neg_lo:[0,1] neg_hi:[0,1]
	v_pk_add_f32 v[6:7], v[6:7], v[82:83] op_sel_hi:[1,0] neg_lo:[0,1] neg_hi:[0,1]
	v_pk_add_f32 v[2:3], v[2:3], v[82:83] op_sel_hi:[1,0] neg_lo:[0,1] neg_hi:[0,1]
	v_pk_add_f32 v[4:5], v[4:5], v[82:83] op_sel_hi:[1,0] neg_lo:[0,1] neg_hi:[0,1]
	v_add_f32_e32 v186, v186, v82
	v_mul_f32_e32 v155, v155, v0
	s_andn2_b64 vcc, exec, s[0:1]
	s_cbranch_vccnz .LBB0_336

; DI void diff_block(const bf16_t* QK, const bf16_t* VT, bf16_t* O, const float* subln, const unsigned* kmx, float lam, int b, int h, int tqb, int wave, int lane, unsigned char* lds) {
;     ...
;         { const bool mine = seen && (ub - slope2 * (float)(t - kb + 1) - m < -150.f);
;           const bool dn = a0 && __all(mine);
;           if (lane == 0) flags[(itn & 1) * 8 + wave] = dn ? 1u : 0u; }
.LBB0_338:
	v_add_u32_e32 v0, s73, v173
	v_subrev_u32_e32 v0, 63, v0
	v_cvt_f32_i32_e32 v0, v0
	v_fma_f32 v0, -v158, v0, v153
	v_sub_f32_e32 v0, v0, v186
	v_cmp_gt_f32_e32 vcc, s69, v0
	s_and_b64 s[2:3], s[54:55], vcc
	s_cmp_eq_u64 s[2:3], exec
	s_cselect_b64 s[2:3], -1, 0
	v_cndmask_b32_e64 v0, 0, 1, s[2:3]
	s_or_b64 exec, exec, s[0:1]
	s_and_b32 s2, s72, 8
	s_and_saveexec_b64 s[0:1], s[4:5]
	s_cbranch_execnz .LBB0_342
	s_branch .LBB0_343

; DI float fexp2(float x) { return __builtin_amdgcn_exp2f(x); }
; DI void softmax_tile(f32x16& s, float& m, float& l, float& alpha) {
;     float mt = fmaxf(fmaxf(s[0], s[1]), fmaxf(s[2], s[3]));
; #pragma unroll
;     for (int j = 4; j < 16; j += 4) mt = fmaxf(mt, fmaxf(fmaxf(s[j], s[j + 1]), fmaxf(s[j + 2], s[j + 3])));
;     mt = fmaxf(mt, __shfl_xor(mt, 32));
;     const float mn = fmaxf(m, mt); alpha = fexp2(m - mn); m = mn;
;     float sum = 0.f;
; #pragma unroll
;     for (int j = 0; j < 16; ++j) { s[j] = fexp2(s[j] - mn); sum += s[j]; }
;     l = l * alpha + sum;
; }
; DI void nsa_block(const bf16_t* P1, const bf16_t* VT1, const bf16_t* KSF, const bf16_t* KC, const bf16_t* VCT, bf16_t* O, const unsigned* kmx, int b, int g, int t0b, int wave, int lane, unsigned char* lds) {
;     ...
;             if (it >= lo_w && it < ntile) {
;                 const int ib = 32 * it;
;                 f32x16 s = qk_lds(B, qf, krow, hf);
; #pragma unroll
;                 for (int j = 0; j < 16; ++j) { const int dist = t - 31 - 16 * (ib + 16 * (j >> 3) + 8 * hf + (j & 7)); s[j] = dist >= 0 ? s[j] * C1 - slope2 * (float)dist : -INFINITY; }
;                 float alpha; softmax_tile(s, m, l, alpha);
.LBB0_985:
	v_cmp_ge_i32_e32 vcc, v0, v64
	v_cmp_lt_i32_e64 s[0:1], v0, v66
	s_and_b64 s[2:3], vcc, s[0:1]
	s_and_saveexec_b64 s[0:1], s[2:3]
	s_cbranch_execz .LBB0_987
	v_and_b32_e32 v0, 1, v27
	v_cmp_eq_u32_e32 vcc, 1, v0
	v_add_u32_e32 v29, 0x170, v26
	v_cvt_f32_u32_e32 v151, v29
	v_cndmask_b32_e32 v0, 0, v193, vcc
	v_add_u32_e32 v23, v178, v0
	ds_read_b128 v[0:3], v23
	ds_read_b128 v[36:39], v23 offset:32
	v_add_u32_e32 v35, 0x160, v26
	s_waitcnt lgkmcnt(1)
	v_mfma_f32_32x32x16_bf16 v[0:15], v[0:3], v[112:115], 0
	v_add_u32_e32 v44, 0x150, v26
	v_cmp_lt_i32_e32 vcc, -1, v29
	v_add_u32_e32 v45, 0x140, v26
	v_add_u32_e32 v46, 0x130, v26
	v_add_u32_e32 v47, 0x50, v26
	ds_read_b128 v[40:43], v23 offset:96
	s_waitcnt lgkmcnt(1)
	v_mfma_f32_32x32x16_bf16 v[0:15], v[36:39], v[116:119], v[0:15]
	ds_read_b128 v[36:39], v23 offset:64
	v_add_u32_e32 v23, 0x120, v26
	s_waitcnt lgkmcnt(0)
	v_mfma_f32_32x32x16_bf16 v[0:15], v[36:39], v[120:123], v[0:15]
	v_add_u32_e32 v36, 0x110, v26
	v_add_u32_e32 v37, 0x100, v26
	v_add_u32_e32 v38, 0x70, v26
	v_add_u32_e32 v39, 0x60, v26
	v_mfma_f32_32x32x16_bf16 v[0:15], v[40:43], v[124:127], v[0:15]
	s_nop 11
	v_mov_b32_e32 v156, v0
	v_pk_mul_f32 v[30:31], v[156:157], v[150:151]
	v_cvt_f32_u32_e32 v151, v35
	v_mov_b32_e32 v156, v1
	v_sub_f32_e32 v0, v30, v31
	v_cndmask_b32_e32 v29, v194, v0, vcc
	v_pk_mul_f32 v[0:1], v[156:157], v[150:151]
	v_cvt_f32_u32_e32 v151, v44
	v_mov_b32_e32 v156, v2
	v_sub_f32_e32 v0, v0, v1
	v_cmp_lt_i32_e32 vcc, -1, v35
	s_nop 1
	v_cndmask_b32_e32 v2, v194, v0, vcc
	v_pk_mul_f32 v[0:1], v[156:157], v[150:151]
	v_cvt_f32_u32_e32 v151, v45
	v_mov_b32_e32 v156, v3
	v_sub_f32_e32 v0, v0, v1
	v_cmp_lt_i32_e32 vcc, -1, v44
	s_nop 1
	v_cndmask_b32_e32 v3, v194, v0, vcc
	v_pk_mul_f32 v[0:1], v[156:157], v[150:151]
	v_cvt_f32_u32_e32 v151, v46
	v_mov_b32_e32 v156, v4
	v_sub_f32_e32 v0, v0, v1
	v_cmp_lt_i32_e32 vcc, -1, v45
	s_nop 1
	v_cndmask_b32_e32 v4, v194, v0, vcc
	v_pk_mul_f32 v[0:1], v[156:157], v[150:151]
	v_cvt_f32_u32_e32 v151, v23
	v_mov_b32_e32 v156, v5
	v_sub_f32_e32 v0, v0, v1
	v_cmp_lt_i32_e32 vcc, -1, v46
	s_nop 1
	v_cndmask_b32_e32 v5, v194, v0, vcc
	v_pk_mul_f32 v[0:1], v[156:157], v[150:151]
	v_cvt_f32_u32_e32 v151, v36
	v_mov_b32_e32 v156, v6
	v_sub_f32_e32 v0, v0, v1
	v_cmp_lt_i32_e32 vcc, -1, v23
	v_add_u32_e32 v23, 64, v26
	s_nop 0
	v_cndmask_b32_e32 v6, v194, v0, vcc
	v_pk_mul_f32 v[0:1], v[156:157], v[150:151]
	v_cvt_f32_u32_e32 v151, v37
	v_mov_b32_e32 v156, v7
	v_sub_f32_e32 v0, v0, v1
	v_cmp_lt_i32_e32 vcc, -1, v36
	s_nop 1
	v_cndmask_b32_e32 v7, v194, v0, vcc
	v_pk_mul_f32 v[0:1], v[156:157], v[150:151]
	v_cvt_f32_u32_e32 v151, v38
	v_mov_b32_e32 v156, v8
	v_sub_f32_e32 v0, v0, v1
	v_cmp_lt_i32_e32 vcc, -1, v37
	s_nop 1
	v_cndmask_b32_e32 v8, v194, v0, vcc
	v_pk_mul_f32 v[0:1], v[156:157], v[150:151]
	v_cvt_f32_u32_e32 v151, v39
	v_mov_b32_e32 v156, v9
	v_sub_f32_e32 v0, v0, v1
	v_cmp_lt_i32_e32 vcc, -1, v38
	s_nop 1
	v_cndmask_b32_e32 v9, v194, v0, vcc
	v_pk_mul_f32 v[0:1], v[156:157], v[150:151]
	v_cvt_f32_u32_e32 v151, v47
	v_mov_b32_e32 v156, v10
	v_sub_f32_e32 v0, v0, v1
	v_cmp_lt_i32_e32 vcc, -1, v39
	s_nop 1
	v_cndmask_b32_e32 v10, v194, v0, vcc
	v_pk_mul_f32 v[0:1], v[156:157], v[150:151]
	v_cvt_f32_u32_e32 v151, v23
	v_sub_f32_e32 v0, v0, v1
	v_cmp_lt_i32_e32 vcc, -1, v47
	v_mov_b32_e32 v156, v11
	v_add_u32_e32 v11, 48, v26
	v_cndmask_b32_e32 v30, v194, v0, vcc
	v_pk_mul_f32 v[0:1], v[156:157], v[150:151]
	v_cvt_f32_u32_e32 v151, v11
	v_sub_f32_e32 v0, v0, v1
	v_cmp_lt_i32_e32 vcc, -1, v23
	v_mov_b32_e32 v156, v12
	v_add_u32_e32 v12, 32, v26
	v_cndmask_b32_e32 v23, v194, v0, vcc
	v_pk_mul_f32 v[0:1], v[156:157], v[150:151]
	v_cvt_f32_u32_e32 v151, v12
	v_sub_f32_e32 v0, v0, v1
	v_cmp_lt_i32_e32 vcc, -1, v11
	v_mov_b32_e32 v156, v13
	v_add_u32_e32 v13, 16, v26
	v_cndmask_b32_e32 v11, v194, v0, vcc
	v_pk_mul_f32 v[0:1], v[156:157], v[150:151]
	v_cvt_f32_u32_e32 v151, v13
	v_sub_f32_e32 v0, v0, v1
	v_cmp_lt_i32_e32 vcc, -1, v12
	v_mov_b32_e32 v156, v14
	v_max_f32_e32 v14, v3, v4
	v_cndmask_b32_e32 v12, v194, v0, vcc
	v_pk_mul_f32 v[0:1], v[156:157], v[150:151]
	v_cvt_f32_u32_e32 v151, v26
	v_sub_f32_e32 v0, v0, v1
	v_cmp_lt_i32_e32 vcc, -1, v13
	v_mov_b32_e32 v156, v15
	v_max_f32_e32 v15, v7, v8
	v_cndmask_b32_e32 v13, v194, v0, vcc
	v_pk_mul_f32 v[0:1], v[156:157], v[150:151]
	v_cmp_lt_i32_e32 vcc, -1, v26
	v_sub_f32_e32 v0, v0, v1
	v_max_f32_e32 v1, v29, v2
	v_cndmask_b32_e32 v0, v194, v0, vcc
	v_max3_f32 v15, v5, v6, v15
	v_max3_f32 v1, v1, v14, v15
	v_max_f32_e32 v14, v30, v23
	v_max_f32_e32 v15, v13, v0
	v_max3_f32 v14, v9, v10, v14
	v_max3_f32 v15, v11, v12, v15
	v_max3_f32 v1, v1, v14, v15
	v_mov_b32_e32 v14, v1
	s_nop 1
	v_permlane32_swap_b32_e32 v1, v14
	v_max3_f32 v1, v67, v1, v14
	v_sub_f32_e32 v15, v29, v1
	v_exp_f32_e32 v15, v15
	v_sub_f32_e32 v2, v2, v1
	v_exp_f32_e32 v2, v2
	v_sub_f32_e32 v3, v3, v1
	v_exp_f32_e32 v3, v3
	v_sub_f32_e32 v4, v4, v1
	v_exp_f32_e32 v4, v4
	v_add_f32_e32 v15, 0, v15
	v_add_f32_e32 v2, v2, v15
	v_add_f32_e32 v2, v3, v2
	v_sub_f32_e32 v3, v5, v1
	v_add_f32_e32 v2, v4, v2
	v_exp_f32_e32 v3, v3
	v_sub_f32_e32 v4, v6, v1
	v_exp_f32_e32 v4, v4
	v_sub_f32_e32 v5, v7, v1
	v_exp_f32_e32 v5, v5
	v_sub_f32_e32 v6, v8, v1
	v_exp_f32_e32 v6, v6
	v_add_f32_e32 v2, v3, v2
	v_sub_f32_e32 v3, v9, v1
	v_add_f32_e32 v2, v4, v2
	v_exp_f32_e32 v3, v3
	v_sub_f32_e32 v4, v10, v1
	v_add_f32_e32 v2, v5, v2
	v_exp_f32_e32 v4, v4
	v_sub_f32_e32 v5, v30, v1
	v_exp_f32_e32 v5, v5
	v_add_f32_e32 v2, v6, v2
	v_sub_f32_e32 v6, v23, v1
	v_exp_f32_e32 v6, v6
	v_add_f32_e32 v2, v3, v2
	v_sub_f32_e32 v3, v11, v1
	v_add_f32_e32 v2, v4, v2
	v_exp_f32_e32 v3, v3
	v_sub_f32_e32 v4, v12, v1
	v_add_f32_e32 v2, v5, v2
	v_exp_f32_e32 v4, v4
	v_sub_f32_e32 v5, v13, v1
	v_exp_f32_e32 v5, v5
	v_sub_f32_e32 v0, v0, v1
	v_sub_f32_e32 v14, v67, v1
	v_add_f32_e32 v2, v6, v2
	v_exp_f32_e32 v0, v0
	v_exp_f32_e32 v14, v14
	v_add_f32_e32 v2, v3, v2
	v_add_f32_e32 v2, v4, v2
	v_add_f32_e32 v2, v5, v2
	v_add_f32_e32 v0, v0, v2
	v_fmac_f32_e32 v0, v34, v14
	v_mov_b32_e32 v34, v0
	v_mov_b32_e32 v67, v1

; DI void nsa_block(const bf16_t* P1, const bf16_t* VT1, const bf16_t* KSF, const bf16_t* KC, const bf16_t* VCT, bf16_t* O, const unsigned* kmx, int b, int g, int t0b, int wave, int lane, unsigned char* lds) {
;     ...
;     for (int k2 = 0; k2 < 8; ++k2) {
;         const int cur = (t0w + k2) >> 6;
;         unsigned long long ma, mb;
;         if (cur < 16) { ma = __ballot(lane <= cur); mb = 0ull; }
;         else {
;             const float va = impA[k2 * 128 + lane] + impB[k2 * 128 + lane], vb = impA[k2 * 128 + 64 + lane] + impB[k2 * 128 + 64 + lane];
;             const int sa = lane, sb = lane + 64;
;             const unsigned ka = (sa >= 1 && sa <= cur - 2) ? __float_as_uint(va) + 1u : 0u, kb = (sb <= cur - 2) ? __float_as_uint(vb) + 1u : 0u;
;             unsigned tau = 0u;
;     ...
;                 const int cnt = __popcll(__ballot(ka >= trial)) + __popcll(__ballot(kb >= trial)); if (cnt >= 13) tau = trial; }
;             const unsigned long long eqA = __ballot(ka == tau), eqB = __ballot(kb == tau);
;             const int need = 13 - __popcll(__ballot(ka > tau)) - __popcll(__ballot(kb > tau));
;             const int rankA = __popcll(eqA & lt_mask), rankB = __popcll(eqA) + __popcll(eqB & lt_mask);
;             const bool selA = (ka > tau) || (ka == tau && rankA < need) || sa == 0 || sa == cur || sa == cur - 1;
;             const bool selB = (kb > tau) || (kb == tau && rankB < need) || sb == cur || sb == cur - 1;
;             ma = __ballot(selA); mb = __ballot(selB);
.LBB0_1019:
	s_movk_i32 s0, 0x3ff
	v_lshrrev_b32_e32 v38, 6, v36
	v_cmp_lt_u32_e32 vcc, s0, v36
	s_and_saveexec_b64 s[0:1], vcc
	s_xor_b64 s[2:3], exec, s[0:1]
	s_cbranch_execz .LBB0_1027
	ds_read2st64_b32 v[32:33], v37 offset1:1
	s_waitcnt lgkmcnt(1)
	ds_read2st64_b32 v[34:35], v37 offset0:16 offset1:17
	s_mov_b64 s[18:19], -1
	s_waitcnt lgkmcnt(0)
	v_add_f32_e32 v32, v32, v34
	v_add_u32_e32 v34, -2, v38
	v_cmp_gt_i32_e32 vcc, v176, v34
	v_add_f32_e32 v33, v33, v35
	s_or_b64 s[0:1], s[4:5], vcc
	v_add_u32_e32 v32, 1, v32
	v_cndmask_b32_e64 v32, v32, 0, s[0:1]
	v_add_u32_e32 v33, 1, v33
	v_cmp_le_i32_e32 vcc, v172, v34
	s_nop 1
	v_cndmask_b32_e32 v33, 0, v33, vcc
	v_cmp_gt_i32_e32 vcc, 0, v32
	s_bcnt1_i32_b64 s0, vcc
	v_cmp_gt_i32_e32 vcc, 0, v33
	s_bcnt1_i32_b64 s1, vcc
	s_add_i32 s1, s1, s0
	s_cmp_gt_u32 s1, 12
	s_cselect_b32 s0, 0x80000000, 0
	s_or_b32 s1, s0, 2.0
	v_cmp_le_u32_e64 s[12:13], s1, v32
	v_cmp_le_u32_e32 vcc, s1, v33
	s_bcnt1_i32_b64 s10, s[12:13]
	s_bcnt1_i32_b64 s11, vcc
	s_add_i32 s11, s11, s10
	s_cmp_gt_u32 s11, 12
	s_cselect_b32 s0, s1, s0
	s_or_b32 s1, s0, 0x20000000
	v_cmp_le_u32_e64 s[12:13], s1, v32
	v_cmp_le_u32_e32 vcc, s1, v33
	s_bcnt1_i32_b64 s10, s[12:13]
	s_bcnt1_i32_b64 s11, vcc
	s_add_i32 s11, s11, s10
	s_cmp_gt_u32 s11, 12
	s_cselect_b32 s0, s1, s0
	s_or_b32 s1, s0, 0x10000000
	v_cmp_le_u32_e64 s[12:13], s1, v32
	v_cmp_le_u32_e32 vcc, s1, v33
	s_bcnt1_i32_b64 s10, s[12:13]
	s_bcnt1_i32_b64 s11, vcc
	s_add_i32 s11, s11, s10
	s_cmp_gt_u32 s11, 12
	s_cselect_b32 s0, s1, s0
	s_or_b32 s1, s0, 0x8000000
	v_cmp_le_u32_e64 s[12:13], s1, v32
	v_cmp_le_u32_e32 vcc, s1, v33
	s_bcnt1_i32_b64 s10, s[12:13]
	s_bcnt1_i32_b64 s11, vcc
	s_add_i32 s11, s11, s10
	s_cmp_gt_u32 s11, 12
	s_cselect_b32 s0, s1, s0
	s_or_b32 s1, s0, 0x4000000
	v_cmp_le_u32_e64 s[12:13], s1, v32
	v_cmp_le_u32_e32 vcc, s1, v33
	s_bcnt1_i32_b64 s10, s[12:13]
	s_bcnt1_i32_b64 s11, vcc
	s_add_i32 s11, s11, s10
	s_cmp_gt_u32 s11, 12
	s_cselect_b32 s0, s1, s0
	s_or_b32 s1, s0, 0x2000000
	v_cmp_le_u32_e64 s[12:13], s1, v32
	v_cmp_le_u32_e32 vcc, s1, v33
	s_bcnt1_i32_b64 s10, s[12:13]
	s_bcnt1_i32_b64 s11, vcc
	s_add_i32 s11, s11, s10
	s_cmp_gt_u32 s11, 12
	s_cselect_b32 s0, s1, s0
	s_or_b32 s1, s0, 0x1000000
	v_cmp_le_u32_e64 s[12:13], s1, v32
	v_cmp_le_u32_e32 vcc, s1, v33
	s_bcnt1_i32_b64 s10, s[12:13]
	s_bcnt1_i32_b64 s11, vcc
	s_add_i32 s11, s11, s10
	s_cmp_gt_u32 s11, 12
	s_cselect_b32 s0, s1, s0
	s_or_b32 s1, s0, 0x800000
	v_cmp_le_u32_e64 s[12:13], s1, v32
	v_cmp_le_u32_e32 vcc, s1, v33
	s_bcnt1_i32_b64 s10, s[12:13]
	s_bcnt1_i32_b64 s11, vcc
	s_add_i32 s11, s11, s10
	s_cmp_gt_u32 s11, 12
	s_cselect_b32 s0, s1, s0
	s_or_b32 s1, s0, 0x400000
	v_cmp_le_u32_e64 s[12:13], s1, v32
	v_cmp_le_u32_e32 vcc, s1, v33
	s_bcnt1_i32_b64 s10, s[12:13]
	s_bcnt1_i32_b64 s11, vcc
	s_add_i32 s11, s11, s10
	s_cmp_gt_u32 s11, 12
	s_cselect_b32 s0, s1, s0
	s_or_b32 s1, s0, 0x200000
	v_cmp_le_u32_e64 s[12:13], s1, v32
	v_cmp_le_u32_e32 vcc, s1, v33
	s_bcnt1_i32_b64 s10, s[12:13]
	s_bcnt1_i32_b64 s11, vcc
	s_add_i32 s11, s11, s10
	s_cmp_gt_u32 s11, 12
	s_cselect_b32 s0, s1, s0
	s_or_b32 s1, s0, 0x100000
	v_cmp_le_u32_e64 s[12:13], s1, v32
	v_cmp_le_u32_e32 vcc, s1, v33
	s_bcnt1_i32_b64 s10, s[12:13]
	s_bcnt1_i32_b64 s11, vcc
	s_add_i32 s11, s11, s10
	s_cmp_gt_u32 s11, 12
	s_cselect_b32 s0, s1, s0
	s_or_b32 s1, s0, 0x80000
	v_cmp_le_u32_e64 s[12:13], s1, v32
	v_cmp_le_u32_e32 vcc, s1, v33
	s_bcnt1_i32_b64 s10, s[12:13]
	s_bcnt1_i32_b64 s11, vcc
	s_add_i32 s11, s11, s10
	s_cmp_gt_u32 s11, 12
	s_cselect_b32 s0, s1, s0
	s_or_b32 s1, s0, 0x40000
	v_cmp_le_u32_e64 s[12:13], s1, v32
	v_cmp_le_u32_e32 vcc, s1, v33
	s_bcnt1_i32_b64 s10, s[12:13]
	s_bcnt1_i32_b64 s11, vcc
	s_add_i32 s11, s11, s10
	s_cmp_gt_u32 s11, 12
	s_cselect_b32 s0, s1, s0
	s_or_b32 s1, s0, 0x20000
	v_cmp_le_u32_e64 s[12:13], s1, v32
	v_cmp_le_u32_e32 vcc, s1, v33
	s_bcnt1_i32_b64 s10, s[12:13]
	s_bcnt1_i32_b64 s11, vcc
	s_add_i32 s11, s11, s10
	s_cmp_gt_u32 s11, 12
	s_cselect_b32 s0, s1, s0
	s_or_b32 s1, s0, 0x10000
	v_cmp_le_u32_e64 s[12:13], s1, v32
	v_cmp_le_u32_e32 vcc, s1, v33
	s_bcnt1_i32_b64 s10, s[12:13]
	s_bcnt1_i32_b64 s11, vcc
	s_add_i32 s11, s11, s10
	s_cmp_gt_u32 s11, 12
	s_cselect_b32 s0, s1, s0
; DI void nsa_block(const bf16_t* P1, const bf16_t* VT1, const bf16_t* KSF, const bf16_t* KC, const bf16_t* VCT, bf16_t* O, const unsigned* kmx, int b, int g, int t0b, int wave, int lane, unsigned char* lds) {
;     ...
;                 const int cnt = __popcll(__ballot(ka >= trial)) + __popcll(__ballot(kb >= trial)); if (cnt >= 13) tau = trial; }
;             const unsigned long long eqA = __ballot(ka == tau), eqB = __ballot(kb == tau);
;             const int need = 13 - __popcll(__ballot(ka > tau)) - __popcll(__ballot(kb > tau));
;             const int rankA = __popcll(eqA & lt_mask), rankB = __popcll(eqA) + __popcll(eqB & lt_mask);
;             const bool selA = (ka > tau) || (ka == tau && rankA < need) || sa == 0 || sa == cur || sa == cur - 1;
;             const bool selB = (kb > tau) || (kb == tau && rankB < need) || sb == cur || sb == cur - 1;
;             ma = __ballot(selA); mb = __ballot(selB);
	s_or_b32 s1, s0, 0x8000
	v_cmp_le_u32_e64 s[12:13], s1, v32
	v_cmp_le_u32_e32 vcc, s1, v33
	s_bcnt1_i32_b64 s10, s[12:13]
	s_bcnt1_i32_b64 s11, vcc
	s_add_i32 s11, s11, s10
	s_cmp_gt_u32 s11, 12
	s_cselect_b32 s0, s1, s0
	s_or_b32 s1, s0, 0x4000
	v_cmp_le_u32_e64 s[12:13], s1, v32
	v_cmp_le_u32_e32 vcc, s1, v33
	s_bcnt1_i32_b64 s10, s[12:13]
	s_bcnt1_i32_b64 s11, vcc
	s_add_i32 s11, s11, s10
	s_cmp_gt_u32 s11, 12
	s_cselect_b32 s0, s1, s0
	s_or_b32 s1, s0, 0x2000
	v_cmp_le_u32_e64 s[12:13], s1, v32
	v_cmp_le_u32_e32 vcc, s1, v33
	s_bcnt1_i32_b64 s10, s[12:13]
	s_bcnt1_i32_b64 s11, vcc
	s_add_i32 s11, s11, s10
	s_cmp_gt_u32 s11, 12
	s_cselect_b32 s0, s1, s0
	s_or_b32 s1, s0, 0x1000
	v_cmp_le_u32_e64 s[12:13], s1, v32
	v_cmp_le_u32_e32 vcc, s1, v33
	s_bcnt1_i32_b64 s10, s[12:13]
	s_bcnt1_i32_b64 s11, vcc
	s_add_i32 s11, s11, s10
	s_cmp_gt_u32 s11, 12
	s_cselect_b32 s0, s1, s0
	s_or_b32 s1, s0, 0x800
	v_cmp_le_u32_e64 s[12:13], s1, v32
	v_cmp_le_u32_e32 vcc, s1, v33
	s_bcnt1_i32_b64 s10, s[12:13]
	s_bcnt1_i32_b64 s11, vcc
	s_add_i32 s11, s11, s10
	s_cmp_gt_u32 s11, 12
	s_cselect_b32 s0, s1, s0
	s_or_b32 s1, s0, 0x400
	v_cmp_le_u32_e64 s[12:13], s1, v32
	v_cmp_le_u32_e32 vcc, s1, v33
	s_bcnt1_i32_b64 s10, s[12:13]
	s_bcnt1_i32_b64 s11, vcc
	s_add_i32 s11, s11, s10
	s_cmp_gt_u32 s11, 12
	s_cselect_b32 s0, s1, s0
	s_or_b32 s1, s0, 0x200
	v_cmp_le_u32_e64 s[12:13], s1, v32
	v_cmp_le_u32_e32 vcc, s1, v33
	s_bcnt1_i32_b64 s10, s[12:13]
	s_bcnt1_i32_b64 s11, vcc
	s_add_i32 s11, s11, s10
	s_cmp_gt_u32 s11, 12
	s_cselect_b32 s0, s1, s0
	s_or_b32 s1, s0, 0x100
	v_cmp_le_u32_e64 s[12:13], s1, v32
	v_cmp_le_u32_e32 vcc, s1, v33
	s_bcnt1_i32_b64 s10, s[12:13]
	s_bcnt1_i32_b64 s11, vcc
	s_add_i32 s11, s11, s10
	s_cmp_gt_u32 s11, 12
	s_cselect_b32 s0, s1, s0
	s_or_b32 s1, s0, 0x80
	v_cmp_le_u32_e64 s[12:13], s1, v32
	v_cmp_le_u32_e32 vcc, s1, v33
	s_bcnt1_i32_b64 s10, s[12:13]
	s_bcnt1_i32_b64 s11, vcc
	s_add_i32 s11, s11, s10
	s_cmp_gt_u32 s11, 12
	s_cselect_b32 s0, s1, s0
	s_or_b32 s1, s0, 64
	v_cmp_le_u32_e64 s[12:13], s1, v32
	v_cmp_le_u32_e32 vcc, s1, v33
	s_bcnt1_i32_b64 s10, s[12:13]
	s_bcnt1_i32_b64 s11, vcc
	s_add_i32 s11, s11, s10
	s_cmp_gt_u32 s11, 12
	s_cselect_b32 s0, s1, s0
	s_or_b32 s1, s0, 32
	v_cmp_le_u32_e64 s[12:13], s1, v32
	v_cmp_le_u32_e32 vcc, s1, v33
	s_bcnt1_i32_b64 s10, s[12:13]
	s_bcnt1_i32_b64 s11, vcc
	s_add_i32 s11, s11, s10
	s_cmp_gt_u32 s11, 12
	s_cselect_b32 s0, s1, s0
	s_or_b32 s1, s0, 16
	v_cmp_le_u32_e64 s[12:13], s1, v32
	v_cmp_le_u32_e32 vcc, s1, v33
	s_bcnt1_i32_b64 s10, s[12:13]
	s_bcnt1_i32_b64 s11, vcc
	s_add_i32 s11, s11, s10
	s_cmp_gt_u32 s11, 12
	s_cselect_b32 s0, s1, s0
	s_or_b32 s1, s0, 8
	v_cmp_le_u32_e64 s[12:13], s1, v32
	v_cmp_le_u32_e32 vcc, s1, v33
	s_bcnt1_i32_b64 s10, s[12:13]
	s_bcnt1_i32_b64 s11, vcc
	s_add_i32 s11, s11, s10
	s_cmp_gt_u32 s11, 12
	s_cselect_b32 s0, s1, s0
	s_or_b32 s1, s0, 4
	v_cmp_le_u32_e64 s[12:13], s1, v32
	v_cmp_le_u32_e32 vcc, s1, v33
	s_bcnt1_i32_b64 s10, s[12:13]
	s_bcnt1_i32_b64 s11, vcc
	s_add_i32 s11, s11, s10
	s_cmp_gt_u32 s11, 12
	s_cselect_b32 s0, s1, s0
	s_or_b32 s1, s0, 2
	v_cmp_le_u32_e64 s[12:13], s1, v32
	v_cmp_le_u32_e32 vcc, s1, v33
	s_bcnt1_i32_b64 s10, s[12:13]
	s_bcnt1_i32_b64 s11, vcc
	s_add_i32 s11, s11, s10
	s_cmp_gt_u32 s11, 12
	s_cselect_b32 s0, s1, s0
	s_or_b32 s1, s0, 1
	v_cmp_le_u32_e64 s[12:13], s1, v32
	v_cmp_le_u32_e32 vcc, s1, v33
	s_bcnt1_i32_b64 s10, s[12:13]
	s_bcnt1_i32_b64 s11, vcc
	s_add_i32 s11, s11, s10
	s_cmp_gt_u32 s11, 12
	s_cselect_b32 s16, s1, s0
	v_cmp_lt_u32_e32 vcc, s16, v32
	s_bcnt1_i32_b64 s17, vcc
	v_cmp_lt_u32_e32 vcc, s16, v33
	v_cmp_ne_u32_e64 s[12:13], s16, v32
	v_cmp_eq_u32_e64 s[10:11], s16, v32
	v_cmp_eq_u32_e64 s[0:1], s16, v33
	v_cmp_ge_u32_e64 s[14:15], s16, v32
	s_bcnt1_i32_b64 s16, vcc
	s_add_i32 s17, s17, s16
	s_sub_i32 s25, 13, s17
	s_and_saveexec_b64 s[16:17], s[14:15]
	s_cbranch_execz .LBB0_1026
	s_mov_b64 s[18:19], 0
	s_and_saveexec_b64 s[14:15], s[12:13]
	s_xor_b64 s[14:15], exec, s[14:15]
	s_cbranch_execz .LBB0_1031
	v_cmp_ne_u32_e64 s[12:13], v176, v38
	s_xor_b64 s[18:19], s[4:5], -1
	s_and_b64 s[12:13], s[18:19], s[12:13]
	s_and_b64 s[18:19], s[12:13], exec
	s_andn2_saveexec_b64 s[42:43], s[14:15]
	s_cbranch_execnz .LBB0_1032

; DI void nsa_block(const bf16_t* P1, const bf16_t* VT1, const bf16_t* KSF, const bf16_t* KC, const bf16_t* VCT, bf16_t* O, const unsigned* kmx, int b, int g, int t0b, int wave, int lane, unsigned char* lds) {
;     ...
;             unsigned long long U = half ? uhi : ulo; const unsigned long long mine = half ? mhi : mlo;
;             U = ((unsigned long long)__builtin_amdgcn_readfirstlane((unsigned)(U >> 32)) << 32) | (unsigned long long)__builtin_amdgcn_readfirstlane((unsigned)U);
;             while (U) {
;                 const int bit = 63 - __builtin_clzll(U); U &= ~(1ull << bit);
;                 const bool colok = (mine >> bit) & 1ull;
;                 const int kb0 = (bit + 64 * half) * 64;
;                 if (__all(seen && (ubq - slope2 * (float)(t - (kb0 + 63)) - m < -150.f))) { stop = true; break; }
.LBB0_1038:
	s_andn2_b64 s[12:13], s[78:79], exec
	s_and_b64 s[14:15], s[42:43], exec
	s_or_b64 s[78:79], s[12:13], s[14:15]
	s_cmp_eq_u64 s[0:1], 0
	s_cbranch_scc1 .LBB0_1036
	s_flbit_i32_b64 s12, s[0:1]
	s_xor_b32 s12, s12, 63
	s_lshl_b32 s13, s12, 6
	s_or_b32 s24, s13, s94
	v_subrev_u32_e32 v64, s24, v163
	v_cvt_f32_i32_e32 v64, v64
	s_lshl_b64 s[18:19], 1, s12
	s_mov_b32 s12, 0xc3160000
	v_fma_f32 v64, -v157, v64, v169
	v_sub_f32_e32 v64, v64, v164
	v_cmp_gt_f32_e32 vcc, s12, v64
	s_and_b64 s[12:13], s[42:43], vcc
	s_cmp_eq_u64 s[12:13], exec
	s_cselect_b64 s[12:13], -1, 0
	s_mov_b64 vcc, s[12:13]
	s_cbranch_vccnz .LBB0_1052
	v_and_b32_e32 v65, s19, v107
	v_and_b32_e32 v64, s18, v106
	s_mov_b64 s[72:73], 0
	v_cmp_eq_u64_e64 s[14:15], 0, v[64:65]
	s_mov_b32 s16, 0
	s_mov_b64 s[88:89], -1
	s_branch .LBB0_1045

; DI float fexp2(float x) { return __builtin_amdgcn_exp2f(x); }
; DI bool soft_core(f32x16& s, float base, float slope2, bool boundary, int tmk8, int wlim, float& mref, bool& seen, float& l, float& alpha) {
;     ...
;     float mt = fmaxf(fmaxf(s[0], s[1]), fmaxf(s[2], s[3]));
; #pragma unroll
;     for (int j = 4; j < 16; j += 4) mt = fmaxf(mt, fmaxf(fmaxf(s[j], s[j + 1]), fmaxf(s[j + 2], s[j + 3])));
;     mt = fmaxf(mt, __shfl_xor(mt, 32));
;     const bool valid = mt > -1e30f, rebase = (mt > 8.f) || (!seen && valid);
;     const bool any = __any(rebase);
;     alpha = 1.f;
;     if (any) {
;         const float delta = rebase ? mt : 0.f;
; #pragma unroll
;         for (int j = 0; j < 16; ++j) s[j] -= delta;
;         alpha = seen ? fexp2(-delta) : 1.f; mref += delta; l *= alpha;
;     }
.LBB0_1048:
	s_or_b64 exec, exec, s[16:17]
	v_max3_f32 v72, v130, v131, v128
	v_max3_f32 v73, v129, v110, v111
	v_max3_f32 v74, v108, v109, v70
	v_max3_f32 v75, v71, v68, v69
	v_max3_f32 v72, v72, v64, v65
	v_max3_f32 v73, v73, v66, v67
	v_max3_f32 v74, v74, v75, v73
	v_max_f32_e32 v72, v72, v74
	v_mov_b32_e32 v73, v72
	s_mov_b64 s[92:93], -1
	s_nop 1
	v_permlane32_swap_b32_e32 v72, v73
	v_max_f32_e32 v72, v72, v73
	v_cmp_lt_f32_e64 s[16:17], s29, v72
	v_cmp_nlt_f32_e32 vcc, s27, v72
	s_and_saveexec_b64 s[90:91], vcc
	s_xor_b64 s[92:93], s[42:43], -1
	s_and_b64 s[92:93], s[16:17], s[92:93]
	s_orn2_b64 s[92:93], s[92:93], exec
	s_or_b64 exec, exec, s[90:91]
	v_cndmask_b32_e64 v73, 0, 1, s[92:93]
	v_cmp_ne_u32_e32 vcc, 0, v73
	s_cmp_lg_u64 vcc, 0
	s_cselect_b64 s[90:91], -1, 0
	s_cbranch_vccz .LBB0_1041
	v_cndmask_b32_e64 v74, 0, v72, s[92:93]
	v_exp_f32_e64 v72, -v74
	v_pk_add_f32 v[130:131], v[130:131], v[74:75] op_sel_hi:[1,0] neg_lo:[0,1] neg_hi:[0,1]
	v_pk_add_f32 v[128:129], v[128:129], v[74:75] op_sel_hi:[1,0] neg_lo:[0,1] neg_hi:[0,1]
	v_pk_add_f32 v[110:111], v[110:111], v[74:75] op_sel_hi:[1,0] neg_lo:[0,1] neg_hi:[0,1]
	v_cndmask_b32_e64 v72, 1.0, v72, s[42:43]
	v_pk_add_f32 v[108:109], v[108:109], v[74:75] op_sel_hi:[1,0] neg_lo:[0,1] neg_hi:[0,1]
	v_pk_add_f32 v[70:71], v[70:71], v[74:75] op_sel_hi:[1,0] neg_lo:[0,1] neg_hi:[0,1]
	v_pk_add_f32 v[68:69], v[68:69], v[74:75] op_sel_hi:[1,0] neg_lo:[0,1] neg_hi:[0,1]
	v_pk_add_f32 v[64:65], v[64:65], v[74:75] op_sel_hi:[1,0] neg_lo:[0,1] neg_hi:[0,1]
	v_pk_add_f32 v[66:67], v[66:67], v[74:75] op_sel_hi:[1,0] neg_lo:[0,1] neg_hi:[0,1]
	v_add_f32_e32 v164, v164, v74
	v_mul_f32_e32 v159, v159, v72
	s_andn2_b64 vcc, exec, s[90:91]
	s_cbranch_vccz .LBB0_1042
	s_branch .LBB0_1043

; DI float fexp2(float x) { return __builtin_amdgcn_exp2f(x); }
; DI bool soft_core(f32x16& s, float base, float slope2, bool boundary, int tmk8, int wlim, float& mref, bool& seen, float& l, float& alpha) {
;     ...
;     float mt = fmaxf(fmaxf(s[0], s[1]), fmaxf(s[2], s[3]));
; #pragma unroll
;     for (int j = 4; j < 16; j += 4) mt = fmaxf(mt, fmaxf(fmaxf(s[j], s[j + 1]), fmaxf(s[j + 2], s[j + 3])));
;     mt = fmaxf(mt, __shfl_xor(mt, 32));
;     const bool valid = mt > -1e30f, rebase = (mt > 8.f) || (!seen && valid);
;     const bool any = __any(rebase);
;     alpha = 1.f;
;     if (any) {
;         const float delta = rebase ? mt : 0.f;
; #pragma unroll
;         for (int j = 0; j < 16; ++j) s[j] -= delta;
;         alpha = seen ? fexp2(-delta) : 1.f; mref += delta; l *= alpha;
;     }
.LBB0_1071:
	s_or_b64 exec, exec, s[2:3]
	v_max3_f32 v108, v168, v169, v166
	v_max3_f32 v109, v167, v96, v97
	v_max3_f32 v110, v100, v101, v98
	v_max3_f32 v111, v99, v102, v103
	v_max3_f32 v108, v108, v104, v105
	v_max3_f32 v109, v109, v106, v107
	v_max3_f32 v110, v110, v111, v109
	v_max_f32_e32 v108, v108, v110
	v_mov_b32_e32 v109, v108
	s_mov_b64 s[2:3], -1
	s_nop 1
	v_permlane32_swap_b32_e32 v108, v109
	v_max_f32_e32 v108, v108, v109
	v_cmp_lt_f32_e64 s[12:13], s29, v108
	v_cmp_nlt_f32_e32 vcc, s27, v108
	s_and_saveexec_b64 s[0:1], vcc
	s_xor_b64 s[2:3], s[78:79], -1
	s_and_b64 s[2:3], s[12:13], s[2:3]
	s_orn2_b64 s[2:3], s[2:3], exec
	s_or_b64 exec, exec, s[0:1]
	v_cndmask_b32_e64 v109, 0, 1, s[2:3]
	v_cmp_ne_u32_e32 vcc, 0, v109
	s_cmp_lg_u64 vcc, 0
	s_cselect_b64 s[0:1], -1, 0
	s_cbranch_vccz .LBB0_1079
	v_cndmask_b32_e64 v110, 0, v108, s[2:3]
	v_exp_f32_e64 v108, -v110
	v_pk_add_f32 v[168:169], v[168:169], v[110:111] op_sel_hi:[1,0] neg_lo:[0,1] neg_hi:[0,1]
	v_pk_add_f32 v[166:167], v[166:167], v[110:111] op_sel_hi:[1,0] neg_lo:[0,1] neg_hi:[0,1]
	v_pk_add_f32 v[100:101], v[100:101], v[110:111] op_sel_hi:[1,0] neg_lo:[0,1] neg_hi:[0,1]
	v_cndmask_b32_e64 v108, 1.0, v108, s[78:79]
	v_pk_add_f32 v[96:97], v[96:97], v[110:111] op_sel_hi:[1,0] neg_lo:[0,1] neg_hi:[0,1]
	v_pk_add_f32 v[98:99], v[98:99], v[110:111] op_sel_hi:[1,0] neg_lo:[0,1] neg_hi:[0,1]
	v_pk_add_f32 v[102:103], v[102:103], v[110:111] op_sel_hi:[1,0] neg_lo:[0,1] neg_hi:[0,1]
	v_pk_add_f32 v[104:105], v[104:105], v[110:111] op_sel_hi:[1,0] neg_lo:[0,1] neg_hi:[0,1]
	v_pk_add_f32 v[106:107], v[106:107], v[110:111] op_sel_hi:[1,0] neg_lo:[0,1] neg_hi:[0,1]
	v_add_f32_e32 v202, v202, v110
	v_mul_f32_e32 v161, v161, v108
	s_andn2_b64 vcc, exec, s[0:1]
	s_cbranch_vccnz .LBB0_1076
